# latent-norm phase row loop software pipelined: next row's load issued before the current row is reduced, wait leaves the previous store outstanding
# baseline (speedup 1.0000x reference)
; __device__ __forceinline__ int otid() { int t = __builtin_amdgcn_workitem_id_x(); asm volatile("" : "+v"(t)); return t; }
; __device__ __forceinline__ int obid() { int t = __builtin_amdgcn_workgroup_id_x(); asm volatile("" : "+s"(t)); return t; }
; __device__ __forceinline__ u32x4 pack8(const float (&f)[8]) { u32x4 w; w.x = pk2(f[0], f[1]); w.y = pk2(f[2], f[3]); w.z = pk2(f[4], f[5]); w.w = pk2(f[6], f[7]); return w; }
; __device__ __forceinline__ void norm_phase(const Params& p, bf16_t* H, int Tc, int l) {
;     const int lane = otid() & 63; const int gw = (obid() * NTHREADS + otid()) >> 6, nw = (gridDim.x * NTHREADS) >> 6;
;     float gCq[8], gCkv[8];
; #pragma unroll
;     for (int i = 0; i < 8; ++i) { gCq[i] = p.cq_gain[l * 256 + (lane & 31) * 8 + i]; gCkv[i] = p.ckv_gain[l * 128 + (lane & 15) * 8 + i]; }
;     const bool isq = lane < 32;
;     const bool act = lane < 48;
;     for (int row = gw; row < Tc; row += nw) {
;         bf16_t* ptr = H + (size_t)row * NP1 + (isq ? CQ + lane * 8 : CKV + (lane - 32) * 8);
;         u32x4 w = act ? *(const u32x4*)ptr : (u32x4){0u, 0u, 0u, 0u};
;         float f[8]; unpack8(w, f); float ss = 0.f;
; #pragma unroll
;         for (int i = 0; i < 8; ++i) ss += f[i] * f[i];
;         ss += __shfl_xor(ss, 1); ss += __shfl_xor(ss, 2); ss += __shfl_xor(ss, 4); ss += __shfl_xor(ss, 8);
;         const float s16 = __shfl_xor(ss, 16);
;         if (isq) ss += s16;
;         const float rs = rsqrtf(ss * (isq ? (1.0f / 256.0f) : (1.0f / 128.0f)) + 1e-6f);
; #pragma unroll
;         for (int i = 0; i < 8; ++i) f[i] = f[i] * rs * (isq ? gCq[i] : gCkv[i]);
;         if (act) *(u32x4*)ptr = pack8(f);
;     }
.LBB0_740:
	s_andn2_b64 vcc, exec, s[30:31]
	s_cbranch_vccnz .LBB0_750
	s_cmp_eq_u32 s11, 1
	s_cbranch_scc0 .LBB0_750
	s_waitcnt lgkmcnt(0)
	v_mov_b32_e32 v0, v192
	v_readlane_b32 s0, v251, 2
	v_mov_b32_e32 v2, v192
	s_nop 0
	v_lshl_add_u32 v2, s0, 9, v2
	v_ashrrev_i32_e32 v8, 6, v2
	v_readlane_b32 s0, v254, 35
	s_nop 1
	v_cmp_gt_i32_e32 vcc, s0, v8
	s_and_saveexec_b64 s[30:31], vcc
	s_cbranch_execz .LBB0_749
	v_lshlrev_b32_e32 v10, 3, v0
	v_and_b32_e32 v9, 63, v0
	v_and_b32_e32 v0, 0x78, v10
	v_readlane_b32 s0, v254, 53
	v_readlane_b32 s40, v251, 22
	v_readlane_b32 s41, v251, 23
	v_or_b32_e32 v0, s0, v0
	v_readlane_b32 s42, v251, 24
	v_readlane_b32 s43, v251, 25
	v_readlane_b32 s44, v251, 26
	v_readlane_b32 s45, v251, 27
	v_readlane_b32 s46, v251, 28
	v_readlane_b32 s47, v251, 29
	v_readlane_b32 s48, v251, 30
	v_readlane_b32 s49, v251, 31
	v_readlane_b32 s50, v251, 32
	v_readlane_b32 s51, v251, 33
	v_readlane_b32 s52, v251, 34
	v_readlane_b32 s53, v251, 35
	v_readlane_b32 s54, v251, 36
	v_readlane_b32 s55, v251, 37
	v_lshl_add_u64 v[6:7], v[0:1], 2, s[40:41]
	v_and_b32_e32 v0, 0xf8, v10
	v_readlane_b32 s0, v254, 45
	v_readlane_b32 s40, v251, 6
	v_readlane_b32 s54, v251, 20
	v_or_b32_e32 v0, s0, v0
	v_readlane_b32 s55, v251, 21
	global_load_dwordx4 v[2:5], v[6:7], off offset:16
	global_load_dwordx4 v[16:19], v[6:7], off
	v_lshl_add_u64 v[6:7], v[0:1], 2, s[54:55]
	global_load_dwordx4 v[20:23], v[6:7], off offset:16
	global_load_dwordx4 v[24:27], v[6:7], off
	v_lshlrev_b32_e32 v0, 3, v9
	v_cmp_gt_u32_e32 vcc, 32, v9
	v_or_b32_e32 v6, 0x1e00, v0
	v_add_u32_e32 v0, 0x1c40, v0
	v_readlane_b32 s1, v254, 54
	v_cndmask_b32_e32 v0, v0, v6, vcc
	v_xor_b32_e32 v6, 1, v197
	v_cmp_lt_i32_e64 s[0:1], v6, v199
	v_cmp_gt_u32_e64 s[36:37], 48, v9
	v_lshlrev_b32_e32 v0, 1, v0
	v_cndmask_b32_e64 v6, v197, v6, s[0:1]
	v_lshlrev_b32_e32 v9, 2, v6
	v_xor_b32_e32 v6, 2, v197
	v_cmp_lt_i32_e64 s[0:1], v6, v199
	v_mov_b32_e32 v7, 0x3b800000
	s_mov_b64 s[38:39], 0
	v_cndmask_b32_e64 v6, v197, v6, s[0:1]
	v_cmp_lt_i32_e64 s[0:1], v250, v199
	v_lshlrev_b32_e32 v10, 2, v6
	v_readlane_b32 s41, v251, 7
	v_cndmask_b32_e64 v6, v197, v250, s[0:1]
	v_lshlrev_b32_e32 v11, 2, v6
	v_xor_b32_e32 v6, 8, v197
	v_cmp_lt_i32_e64 s[0:1], v6, v199
	v_readlane_b32 s42, v251, 8
	v_readlane_b32 s43, v251, 9
	v_cndmask_b32_e64 v6, v197, v6, s[0:1]
	v_cmp_lt_i32_e64 s[0:1], v204, v199
	v_lshlrev_b32_e32 v12, 2, v6
	v_readlane_b32 s44, v251, 10
	v_cndmask_b32_e64 v6, v197, v204, s[0:1]
	v_lshlrev_b32_e32 v13, 2, v6
	v_bfrev_b32_e32 v6, 60
	s_waitcnt vmcnt(0)
	v_cndmask_b32_e32 v14, v6, v7, vcc
	v_readlane_b32 s45, v251, 11
	v_readlane_b32 s46, v251, 12
	v_readlane_b32 s47, v251, 13
	v_readlane_b32 s48, v251, 14
	v_readlane_b32 s49, v251, 15
	v_readlane_b32 s50, v251, 16
	v_readlane_b32 s51, v251, 17
	v_readlane_b32 s52, v251, 18
	v_readlane_b32 s53, v251, 19
	s_waitcnt vmcnt(1)
	v_cndmask_b32_e32 v20, v2, v20, vcc
	v_cndmask_b32_e32 v21, v3, v21, vcc
	v_mad_i64_i32 v[2:3], s[0:1], v8, s4, v[0:1]
	v_cndmask_b32_e32 v15, v5, v23, vcc
	s_waitcnt vmcnt(0)
	v_cndmask_b32_e32 v16, v16, v24, vcc
	v_cndmask_b32_e32 v17, v17, v25, vcc
	v_cndmask_b32_e32 v18, v18, v26, vcc
	v_cndmask_b32_e32 v19, v19, v27, vcc
	v_cndmask_b32_e32 v22, v4, v22, vcc
	v_lshl_add_u64 v[6:7], s[34:35], 0, v[2:3]
	v_mov_b32_e32 v30, 0
	v_mov_b32_e32 v31, 0
	v_mov_b32_e32 v32, 0
	v_mov_b32_e32 v33, 0
	s_and_saveexec_b64 s[0:1], s[36:37]
	global_load_dwordx4 v[30:33], v[6:7], off
	s_mov_b64 exec, s[0:1]
	s_waitcnt vmcnt(0)
	s_branch .Lmy_n1_entry
.LBB0_744:
	s_or_b64 exec, exec, s[40:41]
	v_add_u32_e32 v8, s25, v8
	v_readlane_b32 s0, v254, 35
	s_nop 1
	v_cmp_le_i32_e64 s[0:1], s0, v8
	s_or_b64 s[38:39], s[0:1], s[38:39]
	v_readlane_b32 s0, v254, 17
	v_readlane_b32 s1, v254, 18
	s_nop 1
	v_lshl_add_u64 v[6:7], v[6:7], 0, s[0:1]
	s_andn2_b64 exec, exec, s[38:39]
	s_cbranch_execz .LBB0_749
.LBB0_745:
	s_waitcnt vmcnt(1)
.Lmy_n1_entry:
	v_mov_b64_e32 v[2:3], v[30:31]
	v_mov_b64_e32 v[4:5], v[32:33]
	v_readlane_b32 s0, v254, 17
	v_readlane_b32 s1, v254, 18
	v_add_u32_e32 v29, s25, v8
	s_nop 0
	v_lshl_add_u64 v[34:35], v[6:7], 0, s[0:1]
	v_readlane_b32 s0, v254, 35
	s_nop 1
	v_cmp_gt_i32_e64 s[0:1], s0, v29
	s_and_b64 s[0:1], s[0:1], s[36:37]
	s_and_saveexec_b64 s[40:41], s[0:1]
	global_load_dwordx4 v[30:33], v[34:35], off
	s_mov_b64 exec, s[40:41]
	v_and_b32_e32 v25, 0xffff0000, v2
	v_lshlrev_b32_e32 v26, 16, v2
	v_lshlrev_b32_e32 v24, 16, v3
	v_and_b32_e32 v23, 0xffff0000, v3
	v_lshlrev_b32_e32 v3, 16, v4
	v_and_b32_e32 v2, 0xffff0000, v4
	v_lshlrev_b32_e32 v0, 16, v5
	v_and_b32_e32 v4, 0xffff0000, v5
	v_mul_f32_e32 v5, v25, v25
	v_fmac_f32_e32 v5, v26, v26
	v_fmac_f32_e32 v5, v24, v24
	v_fmac_f32_e32 v5, v23, v23
	v_fmac_f32_e32 v5, v3, v3
	v_fmac_f32_e32 v5, v2, v2
	v_fmac_f32_e32 v5, v0, v0
	v_fmac_f32_e32 v5, v4, v4
	s_waitcnt lgkmcnt(0)
	s_nop 1
	v_add_f32_dpp v5, v5, v5 quad_perm:[1,0,3,2] row_mask:0xf bank_mask:0xf
	s_nop 1
	v_add_f32_dpp v5, v5, v5 quad_perm:[2,3,0,1] row_mask:0xf bank_mask:0xf
	s_nop 1
	v_add_f32_dpp v5, v5, v5 row_half_mirror row_mask:0xf bank_mask:0xf
	s_nop 1
	v_add_f32_dpp v5, v5, v5 row_mirror row_mask:0xf bank_mask:0xf
	s_nop 0
	ds_bpermute_b32 v27, v13, v5
	s_and_saveexec_b64 s[40:41], s[36:37]
	s_cbranch_execz .LBB0_744
	s_waitcnt lgkmcnt(0)
	v_add_f32_e32 v27, v5, v27
	v_cndmask_b32_e32 v5, v5, v27, vcc
	v_fmaak_f32 v5, v14, v5, 0x358637bd
	v_mul_f32_e32 v27, 0x4b800000, v5
	v_cmp_gt_f32_e64 s[0:1], s68, v5
	s_nop 1
	v_cndmask_b32_e64 v5, v5, v27, s[0:1]
	v_rsq_f32_e32 v5, v5
	s_nop 0
	v_mul_f32_e32 v27, 0x45800000, v5
	v_cndmask_b32_e64 v5, v5, v27, s[0:1]
	v_mul_f32_e32 v4, v5, v4
	v_mul_f32_e32 v26, v5, v26
	v_mul_f32_e32 v27, v15, v4
	v_mul_f32_e32 v4, v16, v26
	v_mul_f32_e32 v25, v5, v25
	v_mul_f32_e32 v24, v5, v24
	v_mul_f32_e32 v23, v5, v23
	v_mul_f32_e32 v3, v5, v3
	v_mul_f32_e32 v2, v5, v2
	v_mul_f32_e32 v0, v5, v0
	v_mul_f32_e32 v25, v17, v25
	v_mul_f32_e32 v24, v18, v24
	v_mul_f32_e32 v23, v19, v23
	v_mul_f32_e32 v26, v20, v3
	v_mul_f32_e32 v28, v21, v2
	v_mul_f32_e32 v0, v22, v0
	v_cvt_pk_bf16_f32 v2, v4, v25
	v_cvt_pk_bf16_f32 v3, v24, v23
	v_cvt_pk_bf16_f32 v4, v26, v28
	v_cvt_pk_bf16_f32 v5, v0, v27
	global_store_dwordx4 v[6:7], v[2:5], off
	s_branch .LBB0_744
